# static priority raise for waves 0-3 only in the P7 GEMM (its toggles removed); the other GEMMs keep hipcc's per-segment s_setprio toggles
# baseline (speedup 1.0000x reference)
_Z13mla_hgrn2_fwd6Params:
	s_load_dwordx2 s[64:65], s[0:1], 0x108
	s_load_dwordx4 s[56:59], s[0:1], 0x78
	s_add_u32 s10, s0, 0x108
	s_addc_u32 s11, s1, 0
	v_mov_b32_e32 v1, 0
	s_waitcnt lgkmcnt(0)
	s_cmp_lt_u32 s2, s64
	s_cselect_b32 s3, 12, 18
	s_add_u32 s4, s10, s3
	s_addc_u32 s5, s11, 0
	global_load_ushort v2, v1, s[4:5]
	v_and_b32_e32 v184, 0x3ff, v0
	v_cmp_eq_u32_e64 s[78:79], 0, v184
	v_readfirstlane_b32 s99, v184
	s_waitcnt vmcnt(0)
	v_readfirstlane_b32 s46, v2
	s_and_saveexec_b64 s[4:5], s[78:79]
	s_cbranch_execz .LBB0_2
	s_add_i32 s3, 0, 0x20000
	v_mov_b32_e32 v2, s3
	s_add_i32 s3, 0, 0x20004
	ds_write_b32 v2, v1
	v_mov_b32_e32 v2, s3
	s_add_i32 s3, 0, 0x20008
	ds_write_b32 v2, v1
	v_mov_b32_e32 v2, s3
	s_add_i32 s3, 0, 0x2000c
	ds_write_b32 v2, v1
	v_mov_b32_e32 v2, s3
	ds_write_b32 v2, v1

.LBB0_586:
	s_or_b64 exec, exec, s[8:9]
	v_mov_b32_e32 v8, v184
	s_cmpk_lt_i32 s2, 0x1000
	s_waitcnt lgkmcnt(0)
	s_barrier
	s_cselect_b64 s[8:9], -1, 0
	s_setprio 0
	s_cmp_gt_u32 s99, 0xff
	s_cbranch_scc1 .Lp7_in
	s_setprio 1
.Lp7_in:
	s_cmpk_gt_i32 s2, 0xfff
	v_readfirstlane_b32 s50, v8
	s_cbranch_scc1 .LBB0_592
	s_ashr_i32 s4, s2, 31
	s_lshr_b32 s4, s4, 29
	s_add_i32 s4, s2, s4
	s_and_b32 s5, s4, -8
	s_sub_i32 s5, s2, s5
	s_cmp_gt_i32 s5, -1
	s_cbranch_scc0 .LBB0_589
	s_lshl_b32 s6, s5, 9
	s_cbranch_execz .LBB0_590
	s_branch .LBB0_591

.LBB0_760:
	s_or_b64 exec, exec, s[8:9]
	v_mov_b32_e32 v4, v184
	s_waitcnt lgkmcnt(0)
	s_barrier
	s_setprio 0
	s_cmpk_gt_u32 s2, 0x1fff
	v_ashrrev_i32_e32 v1, 6, v4
	v_and_b32_e32 v6, 63, v4
	v_readfirstlane_b32 s20, v1
	v_and_b32_e32 v0, 0x7f, v4
	v_ashrrev_i32_e32 v5, 7, v4
	s_mov_b32 s9, 0
	s_cbranch_scc1 .LBB0_762
	s_lshl_b32 s5, s2, 16
	s_and_b32 s4, s2, 0xf80
	s_and_b32 s5, s5, 0x10000000
	s_add_u32 s5, s68, s5
	s_addc_u32 s6, s69, 0
	s_lshl_b32 s7, s2, 21
	s_and_b32 s7, s7, 0xfe00000
	v_lshlrev_b32_e32 v2, 4, v5
	s_add_u32 s10, s5, s7
	v_ashrrev_i32_e32 v3, 31, v2
	s_addc_u32 s11, s6, 0
	v_lshlrev_b64 v[2:3], 15, v[2:3]
	v_lshl_add_u64 v[2:3], s[10:11], 0, v[2:3]
	s_lshl_b32 s8, s4, 1
	v_lshl_add_u64 v[8:9], v[2:3], 0, s[8:9]
	v_lshlrev_b32_e32 v2, 1, v0
	v_mov_b32_e32 v3, 0
	v_lshl_add_u64 v[8:9], v[8:9], 0, v[2:3]
	s_movk_i32 s4, 0x2000
	v_add_co_u32_e32 v10, vcc, s4, v8
	s_mov_b32 s4, 0xa000
	s_nop 0
	v_addc_co_u32_e32 v11, vcc, 0, v9, vcc
	v_add_co_u32_e32 v12, vcc, s4, v8
	s_mov_b32 s4, 0x8000
	s_nop 0
	v_addc_co_u32_e32 v13, vcc, 0, v9, vcc
	v_add_co_u32_e32 v14, vcc, s4, v8
	s_mov_b32 s4, 0x12000
	s_nop 0
	v_addc_co_u32_e32 v15, vcc, 0, v9, vcc
	v_add_co_u32_e32 v16, vcc, s4, v8
	s_mov_b32 s4, 0x10000
	s_nop 0
	v_addc_co_u32_e32 v17, vcc, 0, v9, vcc
	v_add_co_u32_e32 v18, vcc, s4, v8
	s_mov_b32 s4, 0x1a000
	s_nop 0
	v_addc_co_u32_e32 v19, vcc, 0, v9, vcc
	v_add_co_u32_e32 v20, vcc, s4, v8
	s_mov_b32 s4, 0x18000
	s_nop 0
	v_addc_co_u32_e32 v21, vcc, 0, v9, vcc
	v_add_co_u32_e32 v22, vcc, s4, v8
	s_mov_b32 s4, 0x22000
	s_nop 0
	v_addc_co_u32_e32 v23, vcc, 0, v9, vcc
	global_load_ushort v7, v[10:11], off
	global_load_ushort v32, v[12:13], off
	global_load_ushort v47, v[14:15], off
	global_load_ushort v33, v[16:17], off
	global_load_ushort v48, v[18:19], off
	global_load_ushort v34, v[20:21], off
	global_load_ushort v49, v[22:23], off
	global_load_ushort v46, v[8:9], off
	v_add_co_u32_e32 v10, vcc, s4, v8
	s_mov_b32 s4, 0x20000
	s_nop 0
	v_addc_co_u32_e32 v11, vcc, 0, v9, vcc
	v_add_co_u32_e32 v12, vcc, s4, v8
	s_mov_b32 s4, 0x2a000
	s_nop 0
	v_addc_co_u32_e32 v13, vcc, 0, v9, vcc
	v_add_co_u32_e32 v14, vcc, s4, v8
	s_mov_b32 s4, 0x28000
	s_nop 0
	v_addc_co_u32_e32 v15, vcc, 0, v9, vcc
	v_add_co_u32_e32 v16, vcc, s4, v8
	s_mov_b32 s4, 0x32000
	s_nop 0
	v_addc_co_u32_e32 v17, vcc, 0, v9, vcc
	v_add_co_u32_e32 v18, vcc, s4, v8
	s_mov_b32 s4, 0x30000
	s_nop 0
	v_addc_co_u32_e32 v19, vcc, 0, v9, vcc
	v_add_co_u32_e32 v20, vcc, s4, v8
	s_mov_b32 s4, 0x3a000
	s_nop 0
	v_addc_co_u32_e32 v21, vcc, 0, v9, vcc
	v_add_co_u32_e32 v22, vcc, s4, v8
	s_mov_b32 s4, 0x38000
	s_nop 0
	v_addc_co_u32_e32 v23, vcc, 0, v9, vcc
	v_add_co_u32_e32 v24, vcc, s4, v8
	s_mov_b32 s4, 0x42000
	s_nop 0
	v_addc_co_u32_e32 v25, vcc, 0, v9, vcc
	global_load_ushort v35, v[10:11], off
	global_load_ushort v50, v[12:13], off
	global_load_ushort v36, v[14:15], off
	global_load_ushort v51, v[16:17], off
	global_load_ushort v37, v[18:19], off
	global_load_ushort v52, v[20:21], off
	global_load_ushort v38, v[22:23], off
	global_load_ushort v53, v[24:25], off
	v_add_co_u32_e32 v10, vcc, s4, v8
	s_mov_b32 s4, 0x40000
	s_nop 0
	v_addc_co_u32_e32 v11, vcc, 0, v9, vcc
	v_add_co_u32_e32 v12, vcc, s4, v8
	s_mov_b32 s4, 0x4a000
	s_nop 0
	v_addc_co_u32_e32 v13, vcc, 0, v9, vcc
	v_add_co_u32_e32 v14, vcc, s4, v8
	s_mov_b32 s4, 0x48000
	s_nop 0
	v_addc_co_u32_e32 v15, vcc, 0, v9, vcc
	v_add_co_u32_e32 v16, vcc, s4, v8
	s_mov_b32 s4, 0x52000
	s_nop 0
	v_addc_co_u32_e32 v17, vcc, 0, v9, vcc
	v_add_co_u32_e32 v18, vcc, s4, v8
	s_mov_b32 s4, 0x50000
	s_nop 0
	v_addc_co_u32_e32 v19, vcc, 0, v9, vcc
	v_add_co_u32_e32 v20, vcc, s4, v8
	s_mov_b32 s4, 0x5a000
	s_nop 0
	v_addc_co_u32_e32 v21, vcc, 0, v9, vcc
	v_add_co_u32_e32 v22, vcc, s4, v8
	s_mov_b32 s4, 0x58000
	s_nop 0
	v_addc_co_u32_e32 v23, vcc, 0, v9, vcc
	v_add_co_u32_e32 v24, vcc, s4, v8
	s_mov_b32 s4, 0x62000
	s_nop 0
	v_addc_co_u32_e32 v25, vcc, 0, v9, vcc
	global_load_ushort v39, v[10:11], off
	global_load_ushort v57, v[12:13], off
	global_load_ushort v40, v[14:15], off
	global_load_ushort v60, v[16:17], off
	global_load_ushort v41, v[18:19], off
	global_load_ushort v62, v[20:21], off
	global_load_ushort v42, v[22:23], off
	global_load_ushort v65, v[24:25], off
	v_add_co_u32_e32 v10, vcc, s4, v8
	s_mov_b32 s4, 0x60000
	s_nop 0
	v_addc_co_u32_e32 v11, vcc, 0, v9, vcc
	v_add_co_u32_e32 v12, vcc, s4, v8
	s_mov_b32 s4, 0x6a000
	s_nop 0
	v_addc_co_u32_e32 v13, vcc, 0, v9, vcc
	v_add_co_u32_e32 v14, vcc, s4, v8
	s_mov_b32 s4, 0x68000
	s_nop 0
	v_addc_co_u32_e32 v15, vcc, 0, v9, vcc
	v_add_co_u32_e32 v16, vcc, s4, v8
	s_mov_b32 s4, 0x72000
	s_nop 0
	v_addc_co_u32_e32 v17, vcc, 0, v9, vcc
	v_add_co_u32_e32 v18, vcc, s4, v8
	s_mov_b32 s4, 0x70000
	s_nop 0
	v_addc_co_u32_e32 v19, vcc, 0, v9, vcc
	v_add_co_u32_e32 v20, vcc, s4, v8
	s_mov_b32 s4, 0x7a000
	s_nop 0
	v_addc_co_u32_e32 v21, vcc, 0, v9, vcc
	v_add_co_u32_e32 v22, vcc, s4, v8
	s_mov_b32 s4, 0x78000
	s_nop 0
	v_addc_co_u32_e32 v23, vcc, 0, v9, vcc
	v_add_co_u32_e32 v8, vcc, s4, v8
	v_lshlrev_b32_e32 v2, 15, v6
	s_nop 0
	v_addc_co_u32_e32 v9, vcc, 0, v9, vcc
	global_load_ushort v43, v[10:11], off
	global_load_ushort v66, v[12:13], off
	global_load_ushort v44, v[14:15], off
	global_load_ushort v77, v[16:17], off
	global_load_ushort v45, v[18:19], off
	global_load_ushort v78, v[20:21], off
	global_load_ushort v54, v[22:23], off
	global_load_ushort v86, v[8:9], off
	v_lshl_add_u64 v[2:3], s[10:11], 0, v[2:3]
	v_lshlrev_b32_e32 v8, 4, v1
	v_lshl_add_u64 v[2:3], v[2:3], 0, s[8:9]
	v_ashrrev_i32_e32 v9, 31, v8
	v_lshl_add_u64 v[2:3], v[8:9], 1, v[2:3]
	s_mov_b64 s[4:5], 0x4000
	v_lshl_add_u64 v[8:9], v[2:3], 0, s[4:5]
	v_add_co_u32_e32 v2, vcc, 0x4000, v2
	s_mov_b32 s4, 0x5040100
	s_nop 0
	v_addc_co_u32_e32 v3, vcc, 0, v3, vcc
	global_load_dwordx4 v[24:27], v[2:3], off
	global_load_dwordx4 v[28:31], v[8:9], off offset:16
	s_waitcnt vmcnt(19)
	v_perm_b32 v21, v38, v37, s4
	v_perm_b32 v20, v36, v35, s4
	v_perm_b32 v23, v34, v33, s4
	v_perm_b32 v22, v32, v7, s4
	s_waitcnt vmcnt(15)
	v_perm_b32 v18, v40, v39, s4
	s_waitcnt vmcnt(11)
	v_perm_b32 v19, v42, v41, s4
	s_waitcnt vmcnt(7)
	v_perm_b32 v16, v44, v43, s4
	s_waitcnt vmcnt(3)
	v_perm_b32 v17, v54, v45, s4
	s_add_u32 s74, s58, 0x4000000
	s_addc_u32 s75, s59, 0
	s_cmpk_gt_i32 s2, 0x1fff
	s_cbranch_scc0 .LBB0_763
	s_branch .LBB0_781
